# EpiProj rope: cos/sin rows of the panel cached in LDS (16 KiB static LDS), rope tiles read LDS instead of global; no vmcnt waits in rope path
# baseline (speedup 1.0000x reference)
.LBB0_111:
	s_lshl_b32 s0, s67, 8
	v_mbcnt_lo_u32_b32 v209, -1, 0
	v_mbcnt_hi_u32_b32 v209, -1, v209
	s_add_i32 s0, s0, s62
	v_and_b32_e32 v122, 15, v209
	v_or_b32_e32 v206, s0, v122
	s_cmp_lg_u32 s67, s45
	v_or_b32_e32 v224, 16, v206
	v_or_b32_e32 v220, 32, v206
	v_or_b32_e32 v216, 48, v206
	v_add_u32_e32 v202, 0xa0, v206
	v_ashrrev_i32_e32 v215, 4, v209
	v_mov_b32_e32 v104, 0x7fc00000
	s_cselect_b64 s[4:5], -1, 0
	s_cmp_eq_u32 s67, s45
	v_ashrrev_i32_e32 v207, 31, v206
	v_add_u32_e32 v210, 0x90, v206
	v_add_u32_e32 v200, 0xb0, v206
	v_ashrrev_i32_e32 v225, 31, v224
	v_ashrrev_i32_e32 v221, 31, v220
	v_ashrrev_i32_e32 v217, 31, v216
	v_ashrrev_i32_e32 v203, 31, v202
	v_mov_b32_e32 v105, 0x7fc00000
	v_mov_b32_e32 v106, 0x7fc00000
	v_mov_b32_e32 v107, 0x7fc00000
	v_mov_b32_e32 v114, 0x7fc00000
	v_mov_b32_e32 v115, 0x7fc00000
	v_mov_b32_e32 v112, 0x7fc00000
	v_mov_b32_e32 v113, 0x7fc00000
	s_mov_b32 s95, 0x28000
	s_cbranch_scc1 .LBB0_113
	v_lshlrev_b32_e32 v40, 2, v215
	v_ashrrev_i32_e32 v41, 31, v40
	v_lshl_add_u64 v[44:45], v[40:41], 2, s[54:55]
	v_lshlrev_b64 v[40:41], 6, v[206:207]
	v_lshlrev_b64 v[42:43], 6, v[224:225]
	v_lshl_add_u64 v[40:41], v[44:45], 0, v[40:41]
	v_lshl_add_u64 v[42:43], v[44:45], 0, v[42:43]
	global_load_dwordx4 v[104:107], v[40:41], off
	global_load_dwordx4 v[112:115], v[42:43], off
	v_lshlrev_b64 v[42:43], 6, v[220:221]
	v_add_co_u32_e32 v40, vcc, s11, v40
	v_lshl_add_u64 v[42:43], v[44:45], 0, v[42:43]
	s_nop 0
	v_addc_co_u32_e32 v41, vcc, 0, v41, vcc
	global_load_dwordx4 v[124:127], v[42:43], off
	global_load_dwordx4 v[56:59], v[40:41], off
	v_lshlrev_b64 v[42:43], 6, v[216:217]
	v_lshl_add_u64 v[42:43], v[44:45], 0, v[42:43]
	global_load_dwordx4 v[152:155], v[42:43], off
	v_ashrrev_i32_e32 v211, 31, v210
	v_lshlrev_b64 v[40:41], 6, v[210:211]
	v_lshl_add_u64 v[40:41], v[44:45], 0, v[40:41]
	global_load_dwordx4 v[60:63], v[40:41], off
	v_ashrrev_i32_e32 v201, 31, v200
	v_lshlrev_b64 v[40:41], 6, v[202:203]
	v_lshlrev_b64 v[46:47], 6, v[200:201]
	v_lshl_add_u64 v[40:41], v[44:45], 0, v[40:41]
	v_lshl_add_u64 v[44:45], v[44:45], 0, v[46:47]
	global_load_dwordx4 v[40:43], v[40:41], off
	s_waitcnt vmcnt(0)
	v_mov_b32_e32 v120, v104
	global_load_dwordx4 v[44:47], v[44:45], off
	v_mov_b32_e32 v121, v112
	v_mov_b32_e32 v112, v105
	v_pk_add_f32 v[104:105], v[120:121], v[112:113]
	v_mov_b32_e32 v112, v106
	v_mov_b32_e32 v113, v114
	v_mov_b32_e32 v114, v107
	v_pk_add_f32 v[106:107], v[112:113], v[114:115]
	v_mov_b32_e32 v114, v126
	v_pk_add_f32 v[104:105], v[104:105], v[106:107]
	ds_swizzle_b32 v106, v104 offset:swizzle(SWAP,16)
	ds_swizzle_b32 v107, v105 offset:swizzle(SWAP,16)
	v_mov_b32_e32 v115, v154
	v_mov_b32_e32 v154, v127
	v_pk_add_f32 v[114:115], v[114:115], v[154:155]
	s_waitcnt lgkmcnt(0)
	v_pk_add_f32 v[104:105], v[104:105], v[106:107]
	s_nop 0
	v_mov_b32_e32 v106, v104
	v_mov_b32_e32 v112, v104
	v_mov_b32_e32 v107, v105
	v_mov_b32_e32 v113, v105
	v_permlane32_swap_b32_e32 v106, v112
	s_nop 0
	v_permlane32_swap_b32_e32 v107, v113
	v_cmp_eq_u32_e32 vcc, v106, v104
	v_cmp_eq_u32_e64 s[40:41], v107, v105
	s_nop 0
	v_cndmask_b32_e32 v106, v106, v112, vcc
	v_cndmask_b32_e64 v107, v107, v113, s[40:41]
	v_pk_add_f32 v[104:105], v[104:105], v[106:107]
	v_mov_b32_e32 v106, v124
	v_mov_b32_e32 v107, v152
	v_mov_b32_e32 v152, v125
	v_pk_add_f32 v[106:107], v[106:107], v[152:153]
	v_mov_b64_e32 v[112:113], s[74:75]
	v_pk_add_f32 v[106:107], v[106:107], v[114:115]
	ds_swizzle_b32 v114, v106 offset:swizzle(SWAP,16)
	ds_swizzle_b32 v115, v107 offset:swizzle(SWAP,16)
	v_pk_fma_f32 v[104:105], v[104:105], s[80:81], v[112:113] op_sel_hi:[1,0,0]
	s_waitcnt lgkmcnt(0)
	v_pk_add_f32 v[106:107], v[106:107], v[114:115]
	s_nop 0
	v_mov_b32_e32 v114, v106
	v_mov_b32_e32 v120, v106
	v_mov_b32_e32 v115, v107
	v_mov_b32_e32 v121, v107
	v_permlane32_swap_b32_e32 v114, v120
	s_nop 0
	v_permlane32_swap_b32_e32 v115, v121
	v_cmp_eq_u32_e32 vcc, v114, v106
	v_cmp_eq_u32_e64 s[40:41], v115, v107
	s_nop 0
	v_cndmask_b32_e32 v114, v114, v120, vcc
	v_cndmask_b32_e64 v115, v115, v121, s[40:41]
	v_pk_add_f32 v[106:107], v[106:107], v[114:115]
	v_mov_b32_e32 v114, v56
	v_mov_b32_e32 v115, v60
	v_mov_b32_e32 v60, v57
	v_pk_add_f32 v[56:57], v[114:115], v[60:61]
	v_mov_b32_e32 v60, v58
	v_mov_b32_e32 v61, v62
	v_mov_b32_e32 v62, v59
	v_pk_add_f32 v[58:59], v[60:61], v[62:63]
	v_pk_fma_f32 v[106:107], v[106:107], s[80:81], v[112:113] op_sel_hi:[1,0,0]
	v_pk_add_f32 v[56:57], v[56:57], v[58:59]
	ds_swizzle_b32 v58, v56 offset:swizzle(SWAP,16)
	ds_swizzle_b32 v59, v57 offset:swizzle(SWAP,16)
	s_waitcnt lgkmcnt(0)
	v_pk_add_f32 v[56:57], v[56:57], v[58:59]
	s_nop 0
	v_mov_b32_e32 v58, v56
	v_mov_b32_e32 v60, v56
	v_mov_b32_e32 v59, v57
	v_mov_b32_e32 v61, v57
	v_permlane32_swap_b32_e32 v58, v60
	s_nop 0
	v_permlane32_swap_b32_e32 v59, v61
	v_cmp_eq_u32_e32 vcc, v58, v56
	v_cmp_eq_u32_e64 s[40:41], v59, v57
	s_nop 0
	v_cndmask_b32_e32 v58, v58, v60, vcc
	v_cndmask_b32_e64 v59, v59, v61, s[40:41]
	v_pk_add_f32 v[56:57], v[56:57], v[58:59]
	s_nop 0
	v_pk_fma_f32 v[114:115], v[56:57], s[80:81], v[112:113] op_sel_hi:[1,0,0]
	v_mov_b32_e32 v56, v40
	s_waitcnt vmcnt(0)
	v_mov_b32_e32 v57, v44
	v_mov_b32_e32 v44, v41
	v_pk_add_f32 v[40:41], v[56:57], v[44:45]
	v_mov_b32_e32 v44, v42
	v_mov_b32_e32 v45, v46
	v_mov_b32_e32 v46, v43
	v_pk_add_f32 v[42:43], v[44:45], v[46:47]
	s_nop 0
	v_pk_add_f32 v[40:41], v[40:41], v[42:43]
	ds_swizzle_b32 v42, v40 offset:swizzle(SWAP,16)
	ds_swizzle_b32 v43, v41 offset:swizzle(SWAP,16)
	s_waitcnt lgkmcnt(0)
	v_pk_add_f32 v[40:41], v[40:41], v[42:43]
	s_nop 0
	v_mov_b32_e32 v42, v40
	v_mov_b32_e32 v44, v40
	v_mov_b32_e32 v43, v41
	v_mov_b32_e32 v45, v41
	v_permlane32_swap_b32_e32 v42, v44
	s_nop 0
	v_permlane32_swap_b32_e32 v43, v45
	v_cmp_eq_u32_e32 vcc, v42, v40
	v_cmp_eq_u32_e64 s[40:41], v43, v41
	s_nop 0
	v_cndmask_b32_e32 v42, v42, v44, vcc
	v_cndmask_b32_e64 v43, v43, v45, s[40:41]
	v_pk_add_f32 v[40:41], v[40:41], v[42:43]
	s_nop 0
	v_pk_fma_f32 v[112:113], v[40:41], s[80:81], v[112:113] op_sel_hi:[1,0,0]
	v_lshrrev_b32_e32 v120, 2, v209
	v_and_b32_e32 v121, 3, v209
	v_lshlrev_b32_e32 v121, 4, v121
	v_add_u32_e32 v120, s62, v120
	v_lshl_add_u32 v120, v120, 6, v121
	s_lshl_b32 s98, s67, 14
	v_add_u32_e32 v122, s98, v120
	v_add_u32_e32 v123, 0x24000, v120
	global_load_dwordx4 v[40:43], v122, s[56:57]
	global_load_dwordx4 v[44:47], v122, s[56:57] offset:1024
	global_load_dwordx4 v[56:59], v122, s[56:57] offset:2048
	global_load_dwordx4 v[60:63], v122, s[56:57] offset:3072
	v_add_u32_e32 v122, 0x2000, v122
	s_waitcnt vmcnt(0)
	ds_write_b128 v123, v[40:43]
	ds_write_b128 v123, v[44:47] offset:1024
	ds_write_b128 v123, v[56:59] offset:2048
	ds_write_b128 v123, v[60:63] offset:3072
	s_waitcnt lgkmcnt(0)
	global_load_dwordx4 v[40:43], v122, s[56:57]
	global_load_dwordx4 v[44:47], v122, s[56:57] offset:1024
	global_load_dwordx4 v[56:59], v122, s[56:57] offset:2048
	global_load_dwordx4 v[60:63], v122, s[56:57] offset:3072
	s_waitcnt vmcnt(0)
	ds_write_b128 v123, v[40:43] offset:8192
	ds_write_b128 v123, v[44:47] offset:9216
	ds_write_b128 v123, v[56:59] offset:10240
	ds_write_b128 v123, v[60:63] offset:11264
	s_waitcnt lgkmcnt(0)

.LBB0_137:
	s_cmp_lt_i32 s44, 6
	s_cselect_b64 s[0:1], -1, 0
	s_and_b64 s[0:1], s[28:29], s[0:1]
	v_cndmask_b32_e64 v104, 0, 1, s[0:1]
	v_cmp_ne_u32_e64 s[42:43], 1, v104
	s_andn2_b64 vcc, exec, s[0:1]
	s_cbranch_vccnz .LBB0_139
	v_lshlrev_b64 v[104:105], 6, v[206:207]
	v_lshl_add_u64 v[104:105], s[56:57], 0, v[104:105]
	v_lshlrev_b64 v[104:105], 6, v[224:225]
	v_lshl_add_u64 v[120:121], s[56:57], 0, v[104:105]
	s_nop 0
	v_and_b32_e32 v120, 0xff, v206
	v_lshlrev_b32_e32 v120, 6, v120
	v_add_u32_e32 v120, 0x24000, v120
	ds_read_b128 v[156:159], v120 offset:48
	ds_read_b128 v[172:175], v120 offset:32
	ds_read_b128 v[152:155], v120 offset:16
	ds_read_b128 v[168:171], v120
	ds_read_b128 v[112:115], v120 offset:1072
	ds_read_b128 v[124:127], v120 offset:1056
	ds_read_b128 v[104:107], v120 offset:1040
	ds_read_b128 v[120:123], v120 offset:1024
.LBB0_139:
	v_cmp_lt_u32_e64 s[46:47], 15, v209
	v_cmp_eq_u32_e64 s[44:45], 1, v215
	v_pk_mul_f32 v[166:167], v[166:167], v[230:231] op_sel_hi:[1,0]
	v_pk_mul_f32 v[234:235], v[164:165], v[230:231] op_sel_hi:[1,0]
	v_pk_mul_f32 v[232:233], v[162:163], v[230:231] op_sel_hi:[1,0]
	s_and_b64 vcc, exec, s[42:43]
	v_pk_mul_f32 v[236:237], v[160:161], v[230:231] op_sel_hi:[1,0]
	s_cbranch_vccnz .LBB0_147
	ds_swizzle_b32 v162, v234 offset:swizzle(SWAP,16)
	ds_swizzle_b32 v160, v236 offset:swizzle(SWAP,16)
	ds_swizzle_b32 v163, v235 offset:swizzle(SWAP,16)
	ds_swizzle_b32 v161, v237 offset:swizzle(SWAP,16)
	ds_swizzle_b32 v240, v166 offset:swizzle(SWAP,16)
	ds_swizzle_b32 v238, v232 offset:swizzle(SWAP,16)
	ds_swizzle_b32 v241, v167 offset:swizzle(SWAP,16)
	ds_swizzle_b32 v239, v233 offset:swizzle(SWAP,16)
	s_and_saveexec_b64 s[0:1], s[46:47]
	s_xor_b64 s[0:1], exec, s[0:1]
	s_cbranch_execz .LBB0_144
	s_and_saveexec_b64 s[4:5], s[44:45]
	s_cbranch_execz .LBB0_143
	s_waitcnt lgkmcnt(0)
	v_pk_mul_f32 v[162:163], v[172:173], v[162:163]
	v_pk_mul_f32 v[164:165], v[174:175], v[240:241]
	v_pk_fma_f32 v[234:235], v[234:235], v[168:169], v[162:163]
	v_pk_mul_f32 v[162:163], v[158:159], v[238:239]
	v_pk_mul_f32 v[160:161], v[156:157], v[160:161]
	v_pk_fma_f32 v[166:167], v[166:167], v[170:171], v[164:165]
	v_pk_fma_f32 v[232:233], v[232:233], v[154:155], v[162:163]
	v_pk_fma_f32 v[236:237], v[236:237], v[152:153], v[160:161]

.LBB0_144:
	s_andn2_saveexec_b64 s[0:1], s[0:1]
	s_cbranch_execz .LBB0_146
	s_waitcnt lgkmcnt(0)
	v_pk_mul_f32 v[162:163], v[172:173], v[162:163]
	v_pk_mul_f32 v[164:165], v[174:175], v[240:241]
	v_pk_fma_f32 v[234:235], v[234:235], v[168:169], v[162:163] neg_lo:[0,0,1] neg_hi:[0,0,1]
	v_pk_mul_f32 v[162:163], v[158:159], v[238:239]
	v_pk_mul_f32 v[160:161], v[156:157], v[160:161]
	v_pk_fma_f32 v[166:167], v[166:167], v[170:171], v[164:165] neg_lo:[0,0,1] neg_hi:[0,0,1]
	v_pk_fma_f32 v[232:233], v[232:233], v[154:155], v[162:163] neg_lo:[0,0,1] neg_hi:[0,0,1]
	v_pk_fma_f32 v[236:237], v[236:237], v[152:153], v[160:161] neg_lo:[0,0,1] neg_hi:[0,0,1]

.LBB0_179:
	s_waitcnt lgkmcnt(0)
	v_cvt_pk_bf16_f32 v96, v116, v117
	v_cvt_pk_bf16_f32 v97, v102, v103
	v_cvt_pk_bf16_f32 v98, v118, v119
	v_cvt_pk_bf16_f32 v99, v110, v111
	s_and_b64 vcc, exec, s[42:43]
	global_store_dwordx4 v[108:109], v[96:99], off offset:256 sc1
	s_cbranch_vccnz .LBB0_181
	s_nop 0
	v_lshlrev_b64 v[96:97], 6, v[220:221]
	v_lshl_add_u64 v[96:97], s[56:57], 0, v[96:97]
	v_lshlrev_b64 v[96:97], 6, v[216:217]
	v_lshl_add_u64 v[108:109], s[56:57], 0, v[96:97]
	s_nop 0
	v_and_b32_e32 v108, 0xff, v206
	v_lshlrev_b32_e32 v108, 6, v108
	v_add_u32_e32 v108, 0x24000, v108
	ds_read_b128 v[148:151], v108 offset:2096
	ds_read_b128 v[164:167], v108 offset:2080
	ds_read_b128 v[144:147], v108 offset:2064
	ds_read_b128 v[160:163], v108 offset:2048
	ds_read_b128 v[100:103], v108 offset:3120
	ds_read_b128 v[116:119], v108 offset:3104
	ds_read_b128 v[96:99], v108 offset:3088
	ds_read_b128 v[108:111], v108 offset:3072
.LBB0_181:
	v_pk_mul_f32 v[142:143], v[142:143], v[226:227] op_sel_hi:[1,0]
	v_pk_mul_f32 v[228:229], v[140:141], v[226:227] op_sel_hi:[1,0]
	v_pk_mul_f32 v[224:225], v[138:139], v[226:227] op_sel_hi:[1,0]
	s_and_b64 vcc, exec, s[42:43]
	v_pk_mul_f32 v[230:231], v[136:137], v[226:227] op_sel_hi:[1,0]
	s_cbranch_vccnz .LBB0_189
	ds_swizzle_b32 v138, v228 offset:swizzle(SWAP,16)
	ds_swizzle_b32 v136, v230 offset:swizzle(SWAP,16)
	ds_swizzle_b32 v139, v229 offset:swizzle(SWAP,16)
	ds_swizzle_b32 v137, v231 offset:swizzle(SWAP,16)
	ds_swizzle_b32 v234, v142 offset:swizzle(SWAP,16)
	ds_swizzle_b32 v232, v224 offset:swizzle(SWAP,16)
	ds_swizzle_b32 v235, v143 offset:swizzle(SWAP,16)
	ds_swizzle_b32 v233, v225 offset:swizzle(SWAP,16)
	s_and_saveexec_b64 s[0:1], s[46:47]
	s_xor_b64 s[0:1], exec, s[0:1]
	s_cbranch_execz .LBB0_186
	s_and_saveexec_b64 s[4:5], s[44:45]
	s_cbranch_execz .LBB0_185
	s_waitcnt lgkmcnt(0)
	v_pk_mul_f32 v[138:139], v[164:165], v[138:139]
	v_pk_mul_f32 v[140:141], v[166:167], v[234:235]
	v_pk_fma_f32 v[228:229], v[228:229], v[160:161], v[138:139]
	v_pk_mul_f32 v[138:139], v[150:151], v[232:233]
	v_pk_mul_f32 v[136:137], v[148:149], v[136:137]
	v_pk_fma_f32 v[142:143], v[142:143], v[162:163], v[140:141]
	v_pk_fma_f32 v[224:225], v[224:225], v[146:147], v[138:139]
	v_pk_fma_f32 v[230:231], v[230:231], v[144:145], v[136:137]

.LBB0_186:
	s_andn2_saveexec_b64 s[0:1], s[0:1]
	s_cbranch_execz .LBB0_188
	s_waitcnt lgkmcnt(0)
	v_pk_mul_f32 v[138:139], v[164:165], v[138:139]
	v_pk_mul_f32 v[140:141], v[166:167], v[234:235]
	v_pk_fma_f32 v[228:229], v[228:229], v[160:161], v[138:139] neg_lo:[0,0,1] neg_hi:[0,0,1]
	v_pk_mul_f32 v[138:139], v[150:151], v[232:233]
	v_pk_mul_f32 v[136:137], v[148:149], v[136:137]
	v_pk_fma_f32 v[142:143], v[142:143], v[162:163], v[140:141] neg_lo:[0,0,1] neg_hi:[0,0,1]
	v_pk_fma_f32 v[224:225], v[224:225], v[146:147], v[138:139] neg_lo:[0,0,1] neg_hi:[0,0,1]
	v_pk_fma_f32 v[230:231], v[230:231], v[144:145], v[136:137] neg_lo:[0,0,1] neg_hi:[0,0,1]

.LBB0_221:
	s_waitcnt lgkmcnt(0)
	v_cvt_pk_bf16_f32 v80, v92, v93
	v_cvt_pk_bf16_f32 v81, v86, v87
	v_cvt_pk_bf16_f32 v82, v94, v95
	v_cvt_pk_bf16_f32 v83, v90, v91
	global_store_dwordx4 v[88:89], v[80:83], off offset:256 sc1
	s_and_b64 vcc, exec, s[42:43]
	s_nop 0
	v_add_u32_e32 v80, 0x80, v206
	v_ashrrev_i32_e32 v81, 31, v80
	s_cbranch_vccnz .LBB0_223
	v_lshlrev_b64 v[82:83], 6, v[80:81]
	v_lshl_add_u64 v[82:83], s[56:57], 0, v[82:83]
	v_lshlrev_b64 v[82:83], 6, v[206:207]
	v_lshl_add_u64 v[82:83], s[56:57], 0, v[82:83]
	s_mov_b64 s[0:1], 0x2400
	v_lshl_add_u64 v[84:85], v[82:83], 0, s[0:1]
	v_add_co_u32_e32 v82, vcc, s11, v82
	s_nop 1
	v_addc_co_u32_e32 v83, vcc, 0, v83, vcc
	v_and_b32_e32 v120, 0xff, v206
	v_lshlrev_b32_e32 v120, 6, v120
	v_add_u32_e32 v120, 0x24000, v120
	ds_read_b128 v[156:159], v120 offset:8240
	ds_read_b128 v[172:175], v120 offset:8224
	ds_read_b128 v[152:155], v120 offset:8208
	ds_read_b128 v[168:171], v120 offset:8192
	ds_read_b128 v[112:115], v120 offset:9264
	ds_read_b128 v[124:127], v120 offset:9248
	ds_read_b128 v[104:107], v120 offset:9232
	ds_read_b128 v[120:123], v120 offset:9216
.LBB0_223:
	v_pk_mul_f32 v[78:79], v[78:79], v[218:219] op_sel_hi:[1,0]
	v_pk_mul_f32 v[84:85], v[76:77], v[218:219] op_sel_hi:[1,0]
	v_pk_mul_f32 v[82:83], v[74:75], v[218:219] op_sel_hi:[1,0]
	s_and_b64 vcc, exec, s[42:43]
	v_pk_mul_f32 v[86:87], v[72:73], v[218:219] op_sel_hi:[1,0]
	s_cbranch_vccnz .LBB0_231
	ds_swizzle_b32 v74, v84 offset:swizzle(SWAP,16)
	ds_swizzle_b32 v72, v86 offset:swizzle(SWAP,16)
	ds_swizzle_b32 v75, v85 offset:swizzle(SWAP,16)
	ds_swizzle_b32 v73, v87 offset:swizzle(SWAP,16)
	ds_swizzle_b32 v90, v78 offset:swizzle(SWAP,16)
	ds_swizzle_b32 v88, v82 offset:swizzle(SWAP,16)
	ds_swizzle_b32 v91, v79 offset:swizzle(SWAP,16)
	ds_swizzle_b32 v89, v83 offset:swizzle(SWAP,16)
	s_and_saveexec_b64 s[0:1], s[46:47]
	s_xor_b64 s[0:1], exec, s[0:1]
	s_cbranch_execz .LBB0_228
	s_and_saveexec_b64 s[4:5], s[44:45]
	s_cbranch_execz .LBB0_227
	s_waitcnt lgkmcnt(0)
	v_pk_mul_f32 v[74:75], v[172:173], v[74:75]
	v_pk_mul_f32 v[76:77], v[174:175], v[90:91]
	v_pk_fma_f32 v[84:85], v[84:85], v[168:169], v[74:75]
	v_pk_mul_f32 v[74:75], v[158:159], v[88:89]
	v_pk_mul_f32 v[72:73], v[156:157], v[72:73]
	v_pk_fma_f32 v[78:79], v[78:79], v[170:171], v[76:77]
	v_pk_fma_f32 v[82:83], v[82:83], v[154:155], v[74:75]
	v_pk_fma_f32 v[86:87], v[86:87], v[152:153], v[72:73]

.LBB0_228:
	s_andn2_saveexec_b64 s[0:1], s[0:1]
	s_cbranch_execz .LBB0_230
	s_waitcnt lgkmcnt(0)
	v_pk_mul_f32 v[74:75], v[172:173], v[74:75]
	v_pk_mul_f32 v[76:77], v[174:175], v[90:91]
	v_pk_fma_f32 v[84:85], v[84:85], v[168:169], v[74:75] neg_lo:[0,0,1] neg_hi:[0,0,1]
	v_pk_mul_f32 v[74:75], v[158:159], v[88:89]
	v_pk_mul_f32 v[72:73], v[156:157], v[72:73]
	v_pk_fma_f32 v[78:79], v[78:79], v[170:171], v[76:77] neg_lo:[0,0,1] neg_hi:[0,0,1]
	v_pk_fma_f32 v[82:83], v[82:83], v[154:155], v[74:75] neg_lo:[0,0,1] neg_hi:[0,0,1]
	v_pk_fma_f32 v[86:87], v[86:87], v[152:153], v[72:73] neg_lo:[0,0,1] neg_hi:[0,0,1]

.LBB0_263:
	s_and_b64 vcc, exec, s[42:43]
	s_waitcnt lgkmcnt(0)
	v_cvt_pk_bf16_f32 v32, v52, v53
	v_cvt_pk_bf16_f32 v33, v38, v39
	v_cvt_pk_bf16_f32 v34, v54, v55
	v_cvt_pk_bf16_f32 v35, v50, v51
	global_store_dwordx4 v[48:49], v[32:35], off offset:256 sc1
	s_cbranch_vccnz .LBB0_265
	s_nop 0
	v_lshlrev_b64 v[32:33], 6, v[202:203]
	v_lshl_add_u64 v[32:33], s[56:57], 0, v[32:33]
	v_lshlrev_b64 v[32:33], 6, v[206:207]
	v_lshl_add_u64 v[32:33], s[56:57], 0, v[32:33]
	v_lshl_add_u64 v[34:35], v[32:33], 0, s[76:77]
	v_add_co_u32_e32 v32, vcc, s11, v32
	s_nop 1
	v_addc_co_u32_e32 v33, vcc, 0, v33, vcc
	v_and_b32_e32 v108, 0xff, v206
	v_lshlrev_b32_e32 v108, 6, v108
	v_add_u32_e32 v108, 0x24000, v108
	ds_read_b128 v[148:151], v108 offset:10288
	ds_read_b128 v[164:167], v108 offset:10272
	ds_read_b128 v[144:147], v108 offset:10256
	ds_read_b128 v[160:163], v108 offset:10240
	ds_read_b128 v[100:103], v108 offset:11312
	ds_read_b128 v[116:119], v108 offset:11296
	ds_read_b128 v[96:99], v108 offset:11280
	ds_read_b128 v[108:111], v108 offset:11264
.LBB0_265:
	v_pk_mul_f32 v[30:31], v[30:31], v[212:213] op_sel_hi:[1,0]
	v_pk_mul_f32 v[34:35], v[28:29], v[212:213] op_sel_hi:[1,0]
	v_pk_mul_f32 v[32:33], v[26:27], v[212:213] op_sel_hi:[1,0]
	s_and_b64 vcc, exec, s[42:43]
	v_pk_mul_f32 v[36:37], v[24:25], v[212:213] op_sel_hi:[1,0]
	s_cbranch_vccnz .LBB0_273
	ds_swizzle_b32 v26, v34 offset:swizzle(SWAP,16)
	ds_swizzle_b32 v24, v36 offset:swizzle(SWAP,16)
	ds_swizzle_b32 v27, v35 offset:swizzle(SWAP,16)
	ds_swizzle_b32 v25, v37 offset:swizzle(SWAP,16)
	ds_swizzle_b32 v48, v30 offset:swizzle(SWAP,16)
	ds_swizzle_b32 v38, v32 offset:swizzle(SWAP,16)
	ds_swizzle_b32 v49, v31 offset:swizzle(SWAP,16)
	ds_swizzle_b32 v39, v33 offset:swizzle(SWAP,16)
	s_and_saveexec_b64 s[0:1], s[46:47]
	s_xor_b64 s[0:1], exec, s[0:1]
	s_cbranch_execz .LBB0_270
	s_and_saveexec_b64 s[4:5], s[44:45]
	s_cbranch_execz .LBB0_269
	s_waitcnt lgkmcnt(0)
	v_pk_mul_f32 v[26:27], v[164:165], v[26:27]
	v_pk_mul_f32 v[28:29], v[166:167], v[48:49]
	v_pk_fma_f32 v[34:35], v[34:35], v[160:161], v[26:27]
	v_pk_mul_f32 v[26:27], v[150:151], v[38:39]
	v_pk_mul_f32 v[24:25], v[148:149], v[24:25]
	v_pk_fma_f32 v[30:31], v[30:31], v[162:163], v[28:29]
	v_pk_fma_f32 v[32:33], v[32:33], v[146:147], v[26:27]
	v_pk_fma_f32 v[36:37], v[36:37], v[144:145], v[24:25]

.LBB0_270:
	s_andn2_saveexec_b64 s[0:1], s[0:1]
	s_cbranch_execz .LBB0_272
	s_waitcnt lgkmcnt(0)
	v_pk_mul_f32 v[26:27], v[164:165], v[26:27]
	v_pk_mul_f32 v[28:29], v[166:167], v[48:49]
	v_pk_fma_f32 v[34:35], v[34:35], v[160:161], v[26:27] neg_lo:[0,0,1] neg_hi:[0,0,1]
	v_pk_mul_f32 v[26:27], v[150:151], v[38:39]
	v_pk_mul_f32 v[24:25], v[148:149], v[24:25]
	v_pk_fma_f32 v[30:31], v[30:31], v[162:163], v[28:29] neg_lo:[0,0,1] neg_hi:[0,0,1]
	v_pk_fma_f32 v[32:33], v[32:33], v[146:147], v[26:27] neg_lo:[0,0,1] neg_hi:[0,0,1]
	v_pk_fma_f32 v[36:37], v[36:37], v[144:145], v[24:25] neg_lo:[0,0,1] neg_hi:[0,0,1]

	.amdhsa_kernel _Z6mk_fwd4Args
		.amdhsa_group_segment_fixed_size 16384
		.amdhsa_private_segment_fixed_size 0
		.amdhsa_kernarg_size 416
		.amdhsa_user_sgpr_count 2
		.amdhsa_user_sgpr_dispatch_ptr 0
		.amdhsa_user_sgpr_queue_ptr 0
		.amdhsa_user_sgpr_kernarg_segment_ptr 1
		.amdhsa_user_sgpr_dispatch_id 0
		.amdhsa_user_sgpr_kernarg_preload_length 0
		.amdhsa_user_sgpr_kernarg_preload_offset 0
		.amdhsa_user_sgpr_private_segment_size 0
		.amdhsa_uses_dynamic_stack 0
		.amdhsa_enable_private_segment 0
		.amdhsa_system_sgpr_workgroup_id_x 1
		.amdhsa_system_sgpr_workgroup_id_y 0
		.amdhsa_system_sgpr_workgroup_id_z 0
		.amdhsa_system_sgpr_workgroup_info 0
		.amdhsa_system_vgpr_workitem_id 2
		.amdhsa_next_free_vgpr 256
		.amdhsa_next_free_sgpr 100
		.amdhsa_accum_offset 256
		.amdhsa_reserve_vcc 1
		.amdhsa_float_round_mode_32 0
		.amdhsa_float_round_mode_16_64 0
		.amdhsa_float_denorm_mode_32 3
		.amdhsa_float_denorm_mode_16_64 3
		.amdhsa_dx10_clamp 1
		.amdhsa_ieee_mode 1
		.amdhsa_fp16_overflow 0
		.amdhsa_tg_split 0
		.amdhsa_exception_fp_ieee_invalid_op 0
		.amdhsa_exception_fp_denorm_src 0
		.amdhsa_exception_fp_ieee_div_zero 0
		.amdhsa_exception_fp_ieee_overflow 0
		.amdhsa_exception_fp_ieee_underflow 0
		.amdhsa_exception_fp_ieee_inexact 0
		.amdhsa_exception_int_div_zero 0
	.end_amdhsa_kernel

amdhsa.kernels:
  - .agpr_count:     0
    .args:
      - .offset:         0
        .size:           160
        .value_kind:     by_value
      - .offset:         160
        .size:           4
        .value_kind:     hidden_block_count_x
      - .offset:         164
        .size:           4
        .value_kind:     hidden_block_count_y
      - .offset:         168
        .size:           4
        .value_kind:     hidden_block_count_z
      - .offset:         172
        .size:           2
        .value_kind:     hidden_group_size_x
      - .offset:         174
        .size:           2
        .value_kind:     hidden_group_size_y
      - .offset:         176
        .size:           2
        .value_kind:     hidden_group_size_z
      - .offset:         178
        .size:           2
        .value_kind:     hidden_remainder_x
      - .offset:         180
        .size:           2
        .value_kind:     hidden_remainder_y
      - .offset:         182
        .size:           2
        .value_kind:     hidden_remainder_z
      - .offset:         200
        .size:           8
        .value_kind:     hidden_global_offset_x
      - .offset:         208
        .size:           8
        .value_kind:     hidden_global_offset_y
      - .offset:         216
        .size:           8
        .value_kind:     hidden_global_offset_z
      - .offset:         224
        .size:           2
        .value_kind:     hidden_grid_dims
      - .offset:         248
        .size:           8
        .value_kind:     hidden_multigrid_sync_arg
      - .offset:         280
        .size:           4
        .value_kind:     hidden_dynamic_lds_size
    .group_segment_fixed_size: 16384
    .kernarg_segment_align: 8
    .kernarg_segment_size: 416
    .language:       OpenCL C
    .language_version:
      - 2
      - 0
    .max_flat_workgroup_size: 512
    .name:           _Z6mk_fwd4Args
    .private_segment_fixed_size: 0
    .sgpr_count:     106
    .sgpr_spill_count: 206
    .symbol:         _Z6mk_fwd4Args.kd
    .uniform_work_group_size: 1
    .uses_dynamic_stack: false
    .vgpr_count:     256
    .vgpr_spill_count: 0
    .wavefront_size: 64
